# MLA loop-edge edit: the l_run and running-max copies moved out of the matrix block (PV / loop tail) into the vector block
# speedup vs baseline: 1.0001x; 1.0001x over previous
; DI unsigned pk2(float lo, float hi) { const f32x2_t v = {lo, hi}; const bf16x2_t b = __builtin_convertvector(v, bf16x2_t); return __builtin_bit_cast(unsigned, b); }
; DI void mla_attn_phase(LAS unsigned char* lds, const bf16_t* Qg, const bf16_t* Kg, const bf16_t* Vtg, bf16_t* MIX) {
;     ...
;                     const float m_new = fmaxf(m_run, mx), alpha = __builtin_amdgcn_exp2f(m_run - m_new); m_run = m_new;
;                     float sum = 0.f;
; #pragma unroll
;                     for (int i = 0; i < 16; ++i) { s0[i] = __builtin_amdgcn_exp2f(s0[i] - m_new); s1[i] = __builtin_amdgcn_exp2f(s1[i] - m_new); sum += s0[i] + s1[i]; }
;                     l_run = l_run * alpha + sum;
;                     if (__any(alpha != 1.f)) {
; #pragma unroll
;                         for (int mt = 0; mt < 4; ++mt)
; #pragma unroll
;                             for (int i = 0; i < 16; ++i) o[mt][i] *= alpha; }
;                     bf16x8 pf[4];
; #pragma unroll
;                     for (int sp = 0; sp < 2; ++sp) { u32x4 p0, p1;
; #pragma unroll
;                         for (int j = 0; j < 4; ++j) { p0[j] = pk2(s0[8 * sp + 2 * j], s0[8 * sp + 2 * j + 1]); p1[j] = pk2(s1[8 * sp + 2 * j], s1[8 * sp + 2 * j + 1]); }
;                         pf[sp] = __builtin_bit_cast(bf16x8, p0); pf[2 + sp] = __builtin_bit_cast(bf16x8, p1); }
.Lmla_nodma:
	v_lshl_add_u64 v[216:217], v[216:217], 0, s[18:19]
	v_lshl_add_u64 v[214:215], v[214:215], 0, s[20:21]
	v_lshl_add_u64 v[212:213], v[212:213], 0, s[2:3]
	v_lshl_add_u64 v[210:211], v[210:211], 0, s[22:23]
	s_cmp_gt_i32 s40, s39
	s_cbranch_scc1 .Lmla_x
	v_sub_f32_e32 v80, v80, v3
	v_sub_f32_e32 v96, v96, v3
	v_exp_f32_e32 v80, v80
	v_exp_f32_e32 v96, v96
	v_sub_f32_e32 v81, v81, v3
	v_sub_f32_e32 v97, v97, v3
	v_exp_f32_e32 v81, v81
	v_exp_f32_e32 v97, v97
	v_sub_f32_e32 v82, v82, v3
	v_sub_f32_e32 v98, v98, v3
	v_exp_f32_e32 v82, v82
	v_exp_f32_e32 v98, v98
	v_sub_f32_e32 v83, v83, v3
	v_sub_f32_e32 v99, v99, v3
	v_exp_f32_e32 v83, v83
	v_exp_f32_e32 v99, v99
	v_add_f32_e32 v218, v80, v96
	v_sub_f32_e32 v84, v84, v3
	v_add_f32_e32 v218, 0, v218
	v_add_f32_e32 v219, v81, v97
	v_exp_f32_e32 v226, v84
	v_sub_f32_e32 v84, v100, v3
	v_add_f32_e32 v218, v219, v218
	v_add_f32_e32 v219, v82, v98
	v_exp_f32_e32 v100, v84
	v_sub_f32_e32 v84, v85, v3
	v_add_f32_e32 v218, v219, v218
	v_add_f32_e32 v219, v83, v99
	v_exp_f32_e32 v227, v84
	v_sub_f32_e32 v84, v101, v3
	v_sub_f32_e32 v86, v86, v3
	v_exp_f32_e32 v101, v84
	v_add_f32_e32 v84, v219, v218
	v_exp_f32_e32 v218, v86
	v_sub_f32_e32 v86, v102, v3
	v_exp_f32_e32 v102, v86
	v_sub_f32_e32 v86, v87, v3
	v_exp_f32_e32 v87, v86
	v_sub_f32_e32 v86, v103, v3
	v_exp_f32_e32 v103, v86
	v_sub_f32_e32 v86, v88, v3
	v_exp_f32_e32 v88, v86
	v_sub_f32_e32 v86, v104, v3
	v_exp_f32_e32 v104, v86
	v_sub_f32_e32 v86, v89, v3
	v_exp_f32_e32 v89, v86
	v_sub_f32_e32 v86, v105, v3
	v_exp_f32_e32 v105, v86
	v_sub_f32_e32 v86, v90, v3
	v_exp_f32_e32 v90, v86
	v_sub_f32_e32 v86, v106, v3
	v_exp_f32_e32 v106, v86
	v_sub_f32_e32 v86, v91, v3
	v_exp_f32_e32 v91, v86
	v_sub_f32_e32 v86, v107, v3
	v_exp_f32_e32 v107, v86
	v_sub_f32_e32 v86, v92, v3
	v_add_f32_e32 v85, v226, v100
	v_exp_f32_e32 v219, v86
	v_sub_f32_e32 v86, v108, v3
	v_add_f32_e32 v84, v85, v84
	v_add_f32_e32 v85, v227, v101
	v_exp_f32_e32 v108, v86
	v_sub_f32_e32 v86, v93, v3
	v_add_f32_e32 v84, v85, v84
	v_add_f32_e32 v85, v218, v102
	v_exp_f32_e32 v234, v86
	v_sub_f32_e32 v86, v109, v3
	v_add_f32_e32 v84, v85, v84
	v_add_f32_e32 v85, v87, v103
	v_exp_f32_e32 v109, v86
	v_sub_f32_e32 v86, v94, v3
	v_add_f32_e32 v84, v85, v84
	v_add_f32_e32 v85, v88, v104
	v_exp_f32_e32 v235, v86
	v_sub_f32_e32 v86, v110, v3
	v_add_f32_e32 v84, v85, v84
	v_add_f32_e32 v85, v89, v105
	v_exp_f32_e32 v110, v86
	v_sub_f32_e32 v86, v95, v3
	v_add_f32_e32 v84, v85, v84
	v_add_f32_e32 v85, v90, v106
	v_exp_f32_e32 v95, v86
	v_sub_f32_e32 v86, v111, v3
	v_add_f32_e32 v84, v85, v84
	v_add_f32_e32 v85, v91, v107
	v_exp_f32_e32 v111, v86
	v_add_f32_e32 v84, v85, v84
	v_add_f32_e32 v85, v219, v108
	v_add_f32_e32 v84, v85, v84
	v_add_f32_e32 v85, v234, v109
	v_add_f32_e32 v84, v85, v84
	v_add_f32_e32 v85, v235, v110
	v_add_f32_e32 v84, v85, v84
	v_add_f32_e32 v85, v95, v111
	v_add_f32_e32 v236, v85, v84
	v_fmac_f32_e32 v236, v233, v0
	v_mov_b32_e32 v233, v236
	v_cvt_pk_bf16_f32 v80, v80, v81
	v_cvt_pk_bf16_f32 v84, v96, v97
	v_cvt_pk_bf16_f32 v81, v82, v83
	v_cvt_pk_bf16_f32 v85, v98, v99
	v_cvt_pk_bf16_f32 v82, v226, v227
	v_cvt_pk_bf16_f32 v86, v100, v101
	v_cvt_pk_bf16_f32 v83, v218, v87
	v_cvt_pk_bf16_f32 v87, v102, v103
	v_cvt_pk_bf16_f32 v88, v88, v89
	v_cvt_pk_bf16_f32 v92, v104, v105
	v_cvt_pk_bf16_f32 v89, v90, v91
	v_cvt_pk_bf16_f32 v93, v106, v107
	v_cvt_pk_bf16_f32 v90, v219, v234
	v_cvt_pk_bf16_f32 v94, v108, v109
	v_cvt_pk_bf16_f32 v91, v235, v95
	v_cvt_pk_bf16_f32 v95, v110, v111
	v_mov_b32_e32 v234, v3

.Lmla_xb:
	s_barrier
	s_cmp_gt_i32 s40, s39
	s_cbranch_scc1 .LBB0_367
	s_waitcnt lgkmcnt(6)
	v_mfma_f32_32x32x16_bf16 v[64:79], v[144:147], v[80:83], v[64:79]
	v_mfma_f32_32x32x16_bf16 v[48:63], v[140:143], v[80:83], v[48:63]
	s_waitcnt lgkmcnt(0)
	v_mfma_f32_32x32x16_bf16 v[32:47], v[148:151], v[80:83], v[32:47]
	v_mfma_f32_32x32x16_bf16 v[16:31], v[152:155], v[80:83], v[16:31]
	ds_read_b128 v[80:83], v1 offset:13376
	ds_read_b128 v[96:99], v1 offset:17984
	ds_read_b128 v[100:103], v1 offset:22592
	ds_read_b128 v[104:107], v1 offset:27200
	v_mfma_f32_32x32x16_bf16 v[64:79], v[136:139], v[88:91], v[64:79]
	v_mfma_f32_32x32x16_bf16 v[48:63], v[12:15], v[88:91], v[48:63]
	v_mfma_f32_32x32x16_bf16 v[32:47], v[4:7], v[88:91], v[32:47]
	v_mfma_f32_32x32x16_bf16 v[16:31], v[8:11], v[88:91], v[16:31]
	ds_read_b128 v[4:7], v1 offset:13408
	ds_read_b128 v[8:11], v1 offset:18016
	ds_read_b128 v[12:15], v1 offset:22624
	ds_read_b128 v[88:91], v1 offset:27232
	s_waitcnt lgkmcnt(4)
	v_mfma_f32_32x32x16_bf16 v[64:79], v[80:83], v[84:87], v[64:79]
	v_mfma_f32_32x32x16_bf16 v[48:63], v[96:99], v[84:87], v[48:63]
	v_mfma_f32_32x32x16_bf16 v[32:47], v[100:103], v[84:87], v[32:47]
	v_mfma_f32_32x32x16_bf16 v[16:31], v[104:107], v[84:87], v[16:31]
	s_waitcnt lgkmcnt(0)
	v_mfma_f32_32x32x16_bf16 v[64:79], v[4:7], v[92:95], v[64:79]
	v_mfma_f32_32x32x16_bf16 v[48:63], v[8:11], v[92:95], v[48:63]
	v_mfma_f32_32x32x16_bf16 v[32:47], v[12:15], v[92:95], v[32:47]
	v_mfma_f32_32x32x16_bf16 v[16:31], v[88:91], v[92:95], v[16:31]
	s_branch .LBB0_371

; #define MLA_DMA(t, slot) do { _Pragma("unroll") for (int i_ = 0; i_ < 4; ++i_) { const bf16_t* src_ = (pisk[i_] ? kbase : vbase) + poff[i_] + (size_t)(t) * pstep[i_]; \
;         __builtin_amdgcn_global_load_lds((const unsigned*)src_, (LAS unsigned*)(lds + (slot) * SLOT + (w + 8 * i_) * 1024), 16, 0, 0); } } while (0)
; DI void mla_attn_phase(LAS unsigned char* lds, const bf16_t* Qg, const bf16_t* Kg, const bf16_t* Vtg, bf16_t* MIX) {
;     ...
;             for (int kt = 0; kt < NT; ++kt) {
;                 const int sl2 = sl == 0 ? 2 : sl - 1;
;                 if (kt + 2 < NT) MLA_DMA(kt + 2, sl2);
;     ...
;                 if (kt + 2 < NT) asm volatile("s_waitcnt vmcnt(4) lgkmcnt(0)" ::: "memory"); else asm volatile("s_waitcnt vmcnt(0) lgkmcnt(0)" ::: "memory");
;                 __builtin_amdgcn_s_barrier(); asm volatile("" ::: "memory");
;                 sl = sl == 2 ? 0 : sl + 1;
.LBB0_371:
	s_add_i32 s41, s41, 1
	s_and_b32 s41, s41, 3
	s_add_i32 s42, s42, 1
	s_add_i32 s40, s40, 64
	s_cmp_eq_u32 s38, s42
	s_cbranch_scc1 .Lmla_exit
	s_branch .LBB0_359
